# combo10 + second-round GQA units split into two KV halves (f32 partial combine through dead H region) to shorten the mixer critical path
# baseline (speedup 1.0000x reference)
; __device__ __forceinline__ int opaque_tid() { int t; asm volatile("v_mov_b32 %0, %1" : "=v"(t) : "v"((int)threadIdx.x)); return t; }
; __global__ void __launch_bounds__(NTHREADS, 2) mega_fwd(Params P) {
;     ...
;             for (;;) {
;                 if (opaque_tid() == 0) qslot[0] = (int)atomicAdd(ctl + 64 * (l + 1), 1u);
;                 __syncthreads();
;                 const int idx = __builtin_amdgcn_readfirstlane(qslot[0]);
;                 __syncthreads();
;                 if (idx >= ntot) break;
;                 if (idx < n_gqa) {
.LBB0_443:
	s_or_b64 exec, exec, s[0:1]
	s_mov_b32 s101, 0
	v_readlane_b32 s0, v254, 42
	s_waitcnt lgkmcnt(0)
	s_barrier
	v_mov_b32_e32 v0, s0
	ds_read_b32 v0, v0
	s_mov_b64 s[0:1], -1
	s_waitcnt lgkmcnt(0)
	s_barrier
	v_readfirstlane_b32 s48, v0
	s_nop 0
	s_mov_b32 s100, 2
	s_cmpk_lt_u32 s48, 0x100
	s_cbranch_scc1 .Lq_done
	s_cmpk_lt_u32 s48, 0x200
	s_cbranch_scc0 .Lq_other
	s_sub_i32 s48, s48, 0x100
	s_and_b32 s100, s48, 1
	s_lshr_b32 s48, s48, 1
	s_add_i32 s48, s48, 0x100
	s_branch .Lq_done

;     const int tid = opaque_tid(), lane = tid & 63, r32 = lane & 31, hi = lane >> 5; const int wid = __builtin_amdgcn_readfirstlane(tid >> 6);
;     const bf16_t* Qw = Q + (long)(wid * QBLK) * PITCH;
;     const unsigned lds0 = (unsigned)(uintptr_t)shm;
;     float* wsf = (float*)(shm + LDS_WS) + wid * 64;
;     const unsigned kvo = (unsigned)((lane * PITCH + wid * 8) * 2);
;     const unsigned vvo = (unsigned)(((16 * (wid & 3) + (lane >> 2)) * PITCH + (wid >> 2) * 32 + (lane & 3) * 8) * 2);
;     const unsigned kdst = lds0 + LDS_K + wid * 1024, vdst = lds0 + LDS_V + wid * 1024;
;     ...
;     const char* Kbase = shm + LDS_K; bf16x8 kf[8];
;     const lds_cptr shm3 = (lds_cptr)shm; const lds_cptr kp0 = shm3 + LDS_K + hi * 1024 + r32 * 16; const lds_cptr vp0 = shm3 + LDS_V + ((lane >> 4) & 1) * 32 + (lane & 3) * 8 + (4 * hi + ((lane & 15) >> 2)) * 64;
;     DMA_K(0, 0); DMA_V(0, 0); DMA_K(1, SLOTB);
;     bf16x8 qr[4];
; #pragma unroll
;     for (int d0 = 0; d0 < 4; ++d0) qr[d0] = *reinterpret_cast<const bf16x8*>(&Qw[(long)r32 * PITCH + d0 * 16 + hi * 8]);
;     float mhat = (MODE == 0) ? bref : 0.f, l_reg = 0.f; f32x16 o[2]; o[0] = f32x16{}; o[1] = f32x16{}; f32x16 negm = f32x16{};
;     if (MODE == 0) { _Pragma("unroll") for (int r = 0; r < 16; ++r) negm[r] = -bref; }
;     if (MODE != 1) asm volatile("" : "+v"(negm));
;     int na_gr = 0, na_rs = 0, na_qc = 0, na_cs = 0;
;     if (MODE == 1) { na_gr = r0 + (wid >> 1); na_rs = min(max(na_gr - 4, 0), 120); na_qc = 32 * (wid & 1) + r32; na_cs = min(max(na_qc - 8, 0), 48); }
;     ...
;     bool resc = false;
;     ...
;     f32x16 pA0, pA1, pB0, pB1;
;     int sl_prev = 0, sl_cur = 0, sl_next = SLOTB;
;     ...
;     DMA_K(2, 2 * SLOTB);
;     WAIT_BAR(3);
;     qkt(pA0, pA1, Kbase, qr, negm, r32, hi); asm volatile("s_nop 15\n\ts_nop 7" : "+v"(pA0), "+v"(pA1));
;     START(pA0, pA1);
; __global__ void __launch_bounds__(NTHREADS, 2) mega_fwd(Params P) {
;     ...
;                     const int qb = idx / 12, r12 = idx % 12, b = r12 / 6, h = r12 % 6; const size_t rb = (size_t)b * RPB;
;                     ap::unit<8, 0>(qkv + (rb + 256 * qb) * DIN + C_QC + 64 * h, qkv + rb * DIN + C_KC + 64 * (h / 3), qkv + rb * DIN + C_VC + 64 * (h / 3),
;                                    omix + (rb + 256 * qb) * DM + 640 + 64 * h, ssb + (rb + 256 * qb) * 4 + 2, 132, (char*)lds, 0, 0, tcos[4096 + l]);
.LBB0_874:
	s_andn2_b64 vcc, exec, s[0:1]
	s_cbranch_vccnz .LBB0_439
	s_mul_hi_i32 s0, s48, 0x2aaaaaab
	s_lshr_b32 s1, s0, 31
	s_ashr_i32 s3, s0, 1
	s_add_i32 s3, s3, s1
	s_mul_i32 s0, s3, 12
	s_sub_i32 s0, s48, s0
	s_mul_i32 s1, s0, 43
	s_bfe_u32 s2, s1, 0x1000f
	s_bfe_u32 s1, s1, 0x80008
	s_add_i32 s1, s1, s2
	s_sext_i32_i8 s18, s1
	s_mul_i32 s1, s1, 6
	s_mul_i32 s9, s18, 0x2100
	s_lshl_b32 s4, s3, 8
	s_sub_i32 s8, s0, s1
	s_ashr_i32 s5, s9, 31
	s_ashr_i32 s6, s4, 31
	s_add_u32 s4, s9, s4
	s_addc_u32 s5, s5, s6
	s_mul_i32 s6, s5, 0x1200
	s_mul_hi_u32 s7, s4, 0x1200
	s_mov_b64 s[0:1], s[76:77]
	s_add_i32 s7, s7, s6
	s_mul_i32 s6, s4, 0x1200
	s_sext_i32_i8 s2, s8
	s_add_u32 s10, s0, s6
	s_addc_u32 s11, s1, s7
	s_lshl_b32 s0, s2, 6
	s_ashr_i32 s1, s0, 31
	s_lshl_b64 s[6:7], s[0:1], 1
	s_add_u32 s26, s10, s6
	s_addc_u32 s27, s11, s7
	s_mov_b64 s[0:1], s[76:77]
	s_mul_i32 s10, s18, 0x2520000
	s_mul_hi_i32 s9, s9, 0x1200
	s_cmp_eq_u32 s100, 2
	s_cselect_b32 s47, 0x7c, 0x3a
	s_cselect_b32 s46, 0, 0x1290000
	s_cmp_eq_u32 s100, 1
	s_cselect_b32 s40, 0x1290000, 0
	s_add_u32 s10, s10, s40
	s_addc_u32 s9, s9, 0
	s_add_u32 s2, s0, s10
	s_addc_u32 s22, s1, s9
	s_bfe_i32 s0, s8, 0x80000
	s_mulk_i32 s0, 0x56
	s_bfe_u32 s1, s0, 0x1000f
	s_bfe_u32 s0, s0, 0x80008
	s_add_i32 s0, s0, s1
	s_sext_i32_i8 s0, s0
	s_lshl_b32 s0, s0, 6
	s_ashr_i32 s1, s0, 31
	s_lshl_b64 s[16:17], s[0:1], 1
	s_add_u32 s30, s2, s16
	s_addc_u32 s34, s22, s17
	s_add_u32 s14, s30, 0xe400300
	s_addc_u32 s15, s34, 0
	s_mov_b64 s[0:1], s[76:77]
	s_add_u32 s23, s0, s10
	s_addc_u32 s24, s1, s9
	s_add_u32 s35, s23, s16
	s_addc_u32 s36, s24, s17
	v_readlane_b32 s20, v252, 9
	s_add_u32 s12, s35, 0xe401100
	s_mov_b64 s[10:11], s[76:77]
	s_mov_b64 s[8:9], s[76:77]
	s_mov_b64 s[0:1], s[76:77]
	v_readlane_b32 s21, v252, 10
	s_addc_u32 s13, s36, 0
	s_lshl_b64 s[20:21], s[20:21], 2
	s_add_u32 s0, s0, s20
	s_addc_u32 s1, s1, s21
	v_mov_b32_e32 v0, s0
	s_mov_b32 s0, 0x184000
	v_mov_b32_e32 v3, s1
	v_add_co_u32_e32 v2, vcc, s0, v0
	v_mov_b32_e32 v194, 0
	s_nop 0
	v_addc_co_u32_e32 v3, vcc, 0, v3, vcc
	flat_load_dword v50, v[2:3]
	v_mov_b32 v14, v214
	s_nop 1
	v_readfirstlane_b32 s25, v14
	s_ashr_i32 s19, s25, 6
	s_cmp_ge_u32 s19, 4
	s_cbranch_scc0 .Lgqa_prio_skip
	s_setprio 1
.Lgqa_prio_skip:
	s_lshl_b32 s0, s19, 5
	s_ashr_i32 s1, s0, 31
	s_mul_i32 s20, s19, 0x24000
	s_mul_hi_i32 s21, s0, 0x1200
	s_add_u32 s28, s26, s20
	s_addc_u32 s29, s27, s21
	s_lshl_b32 s20, s19, 4
	v_and_b32_e32 v15, 63, v14
	v_mov_b32_e32 v0, s20
	v_mad_u32_u24 v193, v15, s80, v0
	v_bfe_u32 v0, v14, 2, 4
	v_and_or_b32 v0, s20, 48, v0
	s_ashr_i32 s20, s25, 3
	s_and_b32 s20, s20, 0x7fffffe0
	v_mov_b32_e32 v2, s20
	v_mad_u32_u24 v0, v0, s81, v2
	v_lshlrev_b32_e32 v2, 3, v14
	v_and_b32_e32 v187, 24, v2
	v_and_b32_e32 v17, 31, v14
	v_or_b32_e32 v0, v0, v187
	s_lshl_b32 s21, s19, 10
	v_lshlrev_b32_e32 v192, 1, v0
	s_cmp_lg_u32 0, -1
	v_mul_u32_u24_e32 v0, 0x900, v17
	v_bfe_u32 v186, v14, 5, 1
	s_cselect_b32 s20, 0, 0
	v_lshlrev_b32_e32 v0, 1, v0
	s_add_i32 s26, s21, s20
	v_lshl_or_b32 v0, v186, 4, v0
	s_add_i32 s20, s26, 0x6000
	s_mov_b32 s27, m0
	s_mov_b32 m0, s26
	s_nop 0
	global_load_lds_dwordx4 v193, s[14:15]
	s_mov_b32 m0, s27
	v_lshl_add_u64 v[2:3], s[28:29], 0, v[0:1]
	s_mov_b32 s27, m0
	s_mov_b32 m0, s20
	s_nop 0
	global_load_lds_dwordx4 v192, s[12:13]
	s_mov_b32 m0, s27
	s_sub_u32 s14, s14, s46
	s_subb_u32 s15, s15, 0
	s_sub_u32 s12, s12, s46
	s_subb_u32 s13, s13, 0
	s_add_u32 s38, s30, 0xe448300
	v_add_co_u32_e32 v4, vcc, s82, v2
	s_addc_u32 s39, s34, 0
	s_add_i32 s27, s26, 0x2000
	s_mov_b32 s31, m0
	s_mov_b32 m0, s27
	s_nop 0
	global_load_lds_dwordx4 v193, s[38:39]
	s_mov_b32 m0, s31
	v_addc_co_u32_e32 v5, vcc, 0, v3, vcc
	flat_load_dwordx4 v[162:165], v[4:5]
	s_mov_b64 s[28:29], 0xe400000
	v_lshl_add_u64 v[2:3], v[2:3], 0, s[28:29]
	flat_load_dwordx4 v[158:161], v[2:3] offset:32
	flat_load_dwordx4 v[154:157], v[2:3] offset:64
	flat_load_dwordx4 v[150:153], v[2:3] offset:96
	s_add_u32 s28, s30, 0xe490300
	v_lshlrev_b32_e32 v0, 10, v186
	v_lshlrev_b32_e32 v4, 4, v17
	s_addc_u32 s29, s34, 0
	s_add_i32 s27, s26, 0x4000
	s_mov_b32 s31, m0
	s_mov_b32 m0, s27
	s_nop 0
	global_load_lds_dwordx4 v193, s[28:29]
	s_mov_b32 m0, s31
	v_add3_u32 v191, 0, v0, v4
	s_waitcnt vmcnt(3) lgkmcnt(0)
	s_barrier
	ds_read_b128 v[2:5], v191
	ds_read_b128 v[6:9], v191 offset:512
	s_waitcnt vmcnt(0) lgkmcnt(0)
	v_xor_b32_e32 v50, 0x80000000, v50
	v_mov_b32_e32 v51, v50
	v_mov_b32_e32 v52, v50
	v_mov_b32_e32 v53, v50
	v_mov_b32_e32 v54, v50
	v_mov_b32_e32 v55, v50
	v_mov_b32_e32 v56, v50
	v_mov_b32_e32 v57, v50
	v_mov_b32_e32 v58, v50
	v_mov_b32_e32 v59, v50
	v_mov_b32_e32 v60, v50
	v_mov_b32_e32 v61, v50
	v_mov_b32_e32 v62, v50
	v_mov_b32_e32 v63, v50
	v_mov_b32_e32 v64, v50
	v_mov_b32_e32 v65, v50
	s_nop 1
	v_mfma_f32_32x32x16_bf16 v[34:49], v[2:5], v[162:165], v[50:65]
	s_add_u32 s38, s30, 0xe4d8300
	s_addc_u32 s39, s34, 0
	s_add_u32 s34, s35, 0xe449100
	s_addc_u32 s35, s36, 0
	v_lshlrev_b32_e32 v0, 1, v14
	v_and_b32_e32 v188, 32, v0
	v_lshlrev_b32_e32 v0, 8, v186
	v_mfma_f32_32x32x16_bf16 v[18:33], v[6:9], v[162:165], v[50:65]
	ds_read_b128 v[2:5], v191 offset:2048
	ds_read_b128 v[6:9], v191 offset:2560
	s_mov_b32 s31, 0
	s_mov_b32 s27, -1
	s_movk_i32 s29, 0x2000
	s_movk_i32 s28, 0x4000
	s_waitcnt lgkmcnt(1)
	v_mfma_f32_32x32x16_bf16 v[34:49], v[2:5], v[158:161], v[34:49]
	s_waitcnt lgkmcnt(0)
	v_mfma_f32_32x32x16_bf16 v[18:33], v[6:9], v[158:161], v[18:33]
	ds_read_b128 v[2:5], v191 offset:4096
	ds_read_b128 v[6:9], v191 offset:4608
	s_waitcnt lgkmcnt(1)
	v_mfma_f32_32x32x16_bf16 v[34:49], v[2:5], v[154:157], v[34:49]
	s_waitcnt lgkmcnt(0)
	v_mfma_f32_32x32x16_bf16 v[18:33], v[6:9], v[154:157], v[18:33]
	ds_read_b128 v[2:5], v191 offset:6144
	ds_read_b128 v[6:9], v191 offset:6656
	s_waitcnt lgkmcnt(1)
	v_mfma_f32_32x32x16_bf16 v[34:49], v[2:5], v[150:153], v[34:49]
	v_lshlrev_b32_e32 v3, 4, v14
	v_add_u32_e32 v2, 0, v188
	v_and_or_b32 v189, v3, s83, v0
	v_add3_u32 v190, v2, v187, v189
	s_waitcnt lgkmcnt(0)
	v_mfma_f32_32x32x16_bf16 v[18:33], v[6:9], v[150:153], v[18:33]
	s_nop 15
	s_nop 7
	s_waitcnt vmcnt(0) lgkmcnt(0)
	s_barrier
; #define WAIT_BAR(N) asm volatile("s_waitcnt vmcnt(" #N ") lgkmcnt(0)\n\ts_barrier" ::: "memory")
; #define RESC() do { if (resc) { asm volatile("s_waitcnt lgkmcnt(0)" ::: "memory"); \
;       _Pragma("unroll") for (int d_ = 0; d_ < 2; ++d_) _Pragma("unroll") for (int r = 0; r < 16; ++r) o[d_][r] *= wsf[crow(r, hi)]; } } while (0)
; #define ROT() do { sl_prev = sl_cur; sl_cur = sl_next; sl_next = (sl_next == (NSLOT - 1) * SLOTB) ? 0 : sl_next + SLOTB; } while (0)
;     ...
;     int t = 1;
;     for (; t + 5 < NT; t += 2) {
;         STEP(pB0, pB1, pA0, pA1, t, true, true, true);     WAIT_BAR(2); RESC(); ROT();
;         STEP(pA0, pA1, pB0, pB1, t + 1, true, true, true); WAIT_BAR(2); RESC(); ROT();
	s_mov_b32 s30, m0
	s_mov_b32 m0, s26
	s_nop 0
	global_load_lds_dwordx4 v193, s[38:39]
	s_mov_b32 m0, s30
	s_add_i32 s30, s26, 0x8000
	s_mov_b32 s36, m0
	s_mov_b32 m0, s30
	s_nop 0
	global_load_lds_dwordx4 v192, s[34:35]
	s_mov_b32 m0, s36
	ds_read_b128 v[98:101], v191 offset:8192
	ds_read_b128 v[170:173], v191 offset:8704
	ds_read_b128 v[174:177], v191 offset:10240
	ds_read_b128 v[166:169], v191 offset:10752
	ds_read_b128 v[142:145], v191 offset:12288
	ds_read_b128 v[138:141], v191 offset:12800
	ds_read_b128 v[134:137], v191 offset:14336
	ds_read_b128 v[130:133], v191 offset:14848
	v_exp_f32_e32 v82, v34
	v_exp_f32_e32 v83, v35
	v_exp_f32_e32 v84, v36
	v_exp_f32_e32 v85, v37
	v_exp_f32_e32 v86, v38
	v_exp_f32_e32 v87, v39
	v_exp_f32_e32 v88, v40
	v_exp_f32_e32 v89, v41
	v_exp_f32_e32 v90, v42
	v_exp_f32_e32 v91, v43
	v_exp_f32_e32 v92, v44
	v_exp_f32_e32 v93, v45
	v_exp_f32_e32 v94, v46
	v_exp_f32_e32 v95, v47
	v_exp_f32_e32 v96, v48
	v_exp_f32_e32 v97, v49
	v_exp_f32_e32 v66, v18
	v_exp_f32_e32 v67, v19
	v_exp_f32_e32 v68, v20
	v_exp_f32_e32 v69, v21
	v_exp_f32_e32 v70, v22
	v_exp_f32_e32 v71, v23
	v_exp_f32_e32 v72, v24
	v_exp_f32_e32 v73, v25
	v_exp_f32_e32 v74, v26
	v_exp_f32_e32 v75, v27
	v_exp_f32_e32 v76, v28
	v_exp_f32_e32 v77, v29
	v_exp_f32_e32 v78, v30
	v_exp_f32_e32 v79, v31
	v_exp_f32_e32 v80, v32
	v_exp_f32_e32 v81, v33
	s_waitcnt vmcnt(2) lgkmcnt(0)
	s_barrier
	v_mov_b32_e32 v18, 0
	v_mov_b32_e32 v19, v194
	v_mov_b32_e32 v20, v194
	v_mov_b32_e32 v21, v194
	v_mov_b32_e32 v22, v194
	v_mov_b32_e32 v23, v194
	v_mov_b32_e32 v24, v194
	v_mov_b32_e32 v25, v194
	v_mov_b32_e32 v26, v194
	v_mov_b32_e32 v27, v194
	v_mov_b32_e32 v28, v194
	v_mov_b32_e32 v29, v194
	v_mov_b32_e32 v30, v194
	v_mov_b32_e32 v31, v194
	v_mov_b32_e32 v32, v194
	v_mov_b32_e32 v33, v194
	v_mov_b32_e32 v34, 0
	v_mov_b32_e32 v35, v194
	v_mov_b32_e32 v36, v194
	v_mov_b32_e32 v37, v194
	v_mov_b32_e32 v38, v194
	v_mov_b32_e32 v39, v194
	v_mov_b32_e32 v40, v194
	v_mov_b32_e32 v41, v194
	v_mov_b32_e32 v42, v194
	v_mov_b32_e32 v43, v194
	v_mov_b32_e32 v44, v194
	v_mov_b32_e32 v45, v194
	v_mov_b32_e32 v46, v194
	v_mov_b32_e32 v47, v194
	v_mov_b32_e32 v48, v194
	v_mov_b32_e32 v49, v194
.LBB0_876:
	v_add_u32_e32 v195, s31, v190
	ds_read_b64_tr_b16 v[182:183], v195 offset:24576
	ds_read_b64_tr_b16 v[184:185], v195 offset:25088
	v_add_f32_e32 v2, v82, v83
	v_add_f32_e32 v2, v84, v2
	v_add_f32_e32 v2, v85, v2
	v_add_f32_e32 v2, v86, v2
	v_add_f32_e32 v2, v87, v2
	v_cvt_pk_bf16_f32 v146, v82, v83
	v_cvt_pk_bf16_f32 v147, v84, v85
	s_waitcnt lgkmcnt(9)
	v_mfma_f32_32x32x16_bf16 v[114:129], v[98:101], v[162:165], v[50:65]
	ds_read_b64_tr_b16 v[178:179], v195 offset:28672
	ds_read_b64_tr_b16 v[180:181], v195 offset:29184
	s_waitcnt lgkmcnt(10)
	v_mfma_f32_32x32x16_bf16 v[98:113], v[170:173], v[162:165], v[50:65]
	v_add_f32_e32 v2, v88, v2
	v_add_f32_e32 v2, v89, v2
	v_add_f32_e32 v2, v90, v2
	v_add_f32_e32 v2, v91, v2
	v_cvt_pk_bf16_f32 v148, v86, v87
	v_cvt_pk_bf16_f32 v149, v88, v89
	ds_read_b64_tr_b16 v[82:83], v195 offset:25600
	ds_read_b64_tr_b16 v[84:85], v195 offset:26112
	v_add_f32_e32 v2, v92, v2
	v_add_f32_e32 v2, v93, v2
	v_add_f32_e32 v2, v94, v2
	v_add_f32_e32 v2, v95, v2
	v_cvt_pk_bf16_f32 v10, v90, v91
	v_cvt_pk_bf16_f32 v11, v92, v93
	s_waitcnt lgkmcnt(11)
	v_mfma_f32_32x32x16_bf16 v[114:129], v[174:177], v[158:161], v[114:129]
	ds_read_b64_tr_b16 v[86:87], v195 offset:29696
	ds_read_b64_tr_b16 v[88:89], v195 offset:30208
	s_waitcnt lgkmcnt(12)
	v_mfma_f32_32x32x16_bf16 v[98:113], v[166:169], v[158:161], v[98:113]
	v_add_f32_e32 v2, v96, v2
	v_add_f32_e32 v2, v97, v2
	v_add_f32_e32 v2, v66, v2
	v_add_f32_e32 v2, v67, v2
	v_cvt_pk_bf16_f32 v12, v94, v95
	v_cvt_pk_bf16_f32 v13, v96, v97
	ds_read_b64_tr_b16 v[90:91], v195 offset:26624
	ds_read_b64_tr_b16 v[92:93], v195 offset:27136
	v_add_f32_e32 v2, v68, v2
	v_add_f32_e32 v2, v69, v2
	v_add_f32_e32 v2, v70, v2
	v_add_f32_e32 v2, v71, v2
	v_cvt_pk_bf16_f32 v6, v66, v67
	v_cvt_pk_bf16_f32 v7, v68, v69
	s_waitcnt lgkmcnt(13)
	v_mfma_f32_32x32x16_bf16 v[114:129], v[142:145], v[154:157], v[114:129]
	ds_read_b64_tr_b16 v[66:67], v195 offset:30720
	ds_read_b64_tr_b16 v[68:69], v195 offset:31232
	s_waitcnt lgkmcnt(14)
	v_mfma_f32_32x32x16_bf16 v[98:113], v[138:141], v[154:157], v[98:113]
	v_add_f32_e32 v2, v72, v2
	v_add_f32_e32 v2, v73, v2
	v_add_f32_e32 v2, v74, v2
	v_add_f32_e32 v2, v75, v2
	v_cvt_pk_bf16_f32 v8, v70, v71
	v_cvt_pk_bf16_f32 v9, v72, v73
	ds_read_b64_tr_b16 v[70:71], v195 offset:27648
	ds_read_b64_tr_b16 v[72:73], v195 offset:28160
	v_add_f32_e32 v2, v76, v2
	v_add_f32_e32 v2, v77, v2
	v_add_f32_e32 v2, v78, v2
	v_add_f32_e32 v94, v79, v2
	v_cvt_pk_bf16_f32 v2, v74, v75
	v_cvt_pk_bf16_f32 v3, v76, v77
	s_waitcnt lgkmcnt(14)
	v_mfma_f32_32x32x16_bf16 v[114:129], v[134:137], v[150:153], v[114:129]
	ds_read_b64_tr_b16 v[74:75], v195 offset:31744
	ds_read_b64_tr_b16 v[76:77], v195 offset:32256
	v_mfma_f32_32x32x16_bf16 v[98:113], v[130:133], v[150:153], v[98:113]
	v_add_f32_e32 v4, v80, v94
	v_add_f32_e32 v4, v81, v4
	v_add_f32_e32 v195, 0, v4
	v_cvt_pk_bf16_f32 v4, v78, v79
	v_cvt_pk_bf16_f32 v5, v80, v81
	s_add_u32 s31, s2, s16
	s_addc_u32 s34, s22, s17
	s_add_u32 s36, s31, 0xe520300
	s_addc_u32 s37, s34, 0
	s_add_i32 s30, s29, s26
	s_mov_b32 s35, m0
	s_mov_b32 m0, s30
	s_nop 0
	global_load_lds_dwordx4 v193, s[36:37]
	s_mov_b32 m0, s35
	s_add_u32 s35, s23, s16
	s_addc_u32 s36, s24, s17
	s_add_u32 s38, s35, 0xe491100
	s_addc_u32 s39, s36, 0
	s_add_i32 s30, s28, s20
	s_mov_b32 s37, m0
	s_mov_b32 m0, s30
	s_nop 0
	global_load_lds_dwordx4 v192, s[38:39]
	s_mov_b32 m0, s37
	s_waitcnt lgkmcnt(14)
; #define WAIT_BAR(N) asm volatile("s_waitcnt vmcnt(" #N ") lgkmcnt(0)\n\ts_barrier" ::: "memory")
; #define RESC() do { if (resc) { asm volatile("s_waitcnt lgkmcnt(0)" ::: "memory"); \
;       _Pragma("unroll") for (int d_ = 0; d_ < 2; ++d_) _Pragma("unroll") for (int r = 0; r < 16; ++r) o[d_][r] *= wsf[crow(r, hi)]; } } while (0)
; #define ROT() do { sl_prev = sl_cur; sl_cur = sl_next; sl_next = (sl_next == (NSLOT - 1) * SLOTB) ? 0 : sl_next + SLOTB; } while (0)
;     ...
;     int t = 1;
;     for (; t + 5 < NT; t += 2) {
;         STEP(pB0, pB1, pA0, pA1, t, true, true, true);     WAIT_BAR(2); RESC(); ROT();
;         STEP(pA0, pA1, pB0, pB1, t + 1, true, true, true); WAIT_BAR(2); RESC(); ROT();
	v_mfma_f32_32x32x16_bf16 v[18:33], v[146:149], v[182:185], v[18:33]
	v_exp_f32_e32 v114, v114
	v_exp_f32_e32 v115, v115
	v_exp_f32_e32 v116, v116
	v_exp_f32_e32 v117, v117
	s_waitcnt lgkmcnt(12)
	v_mfma_f32_32x32x16_bf16 v[34:49], v[146:149], v[178:181], v[34:49]
	v_exp_f32_e32 v118, v118
	v_exp_f32_e32 v119, v119
	v_exp_f32_e32 v120, v120
	v_exp_f32_e32 v121, v121
	v_add_u32_e32 v94, s28, v191
	ds_read_b128 v[78:81], v94
	ds_read_b128 v[134:137], v94 offset:512
	s_waitcnt lgkmcnt(12)
	v_mfma_f32_32x32x16_bf16 v[18:33], v[10:13], v[82:85], v[18:33]
	v_exp_f32_e32 v122, v122
	v_exp_f32_e32 v123, v123
	v_exp_f32_e32 v124, v124
	v_exp_f32_e32 v125, v125
	ds_read_b128 v[138:141], v94 offset:2048
	ds_read_b128 v[142:145], v94 offset:2560
	s_waitcnt lgkmcnt(12)
	v_mfma_f32_32x32x16_bf16 v[34:49], v[10:13], v[86:89], v[34:49]
	v_exp_f32_e32 v126, v126
	v_exp_f32_e32 v127, v127
	v_exp_f32_e32 v128, v128
	v_exp_f32_e32 v129, v129
	ds_read_b128 v[166:169], v94 offset:4096
	ds_read_b128 v[170:173], v94 offset:4608
	s_waitcnt lgkmcnt(12)
	v_mfma_f32_32x32x16_bf16 v[18:33], v[6:9], v[90:93], v[18:33]
	v_exp_f32_e32 v98, v98
	v_exp_f32_e32 v99, v99
	v_exp_f32_e32 v100, v100
	v_exp_f32_e32 v101, v101
	ds_read_b128 v[174:177], v94 offset:6144
	ds_read_b128 v[130:133], v94 offset:6656
	s_waitcnt lgkmcnt(12)
	v_mfma_f32_32x32x16_bf16 v[34:49], v[6:9], v[66:69], v[34:49]
	v_exp_f32_e32 v102, v102
	v_exp_f32_e32 v103, v103
	v_exp_f32_e32 v104, v104
	v_exp_f32_e32 v105, v105
	s_waitcnt lgkmcnt(10)
	v_mfma_f32_32x32x16_bf16 v[18:33], v[2:5], v[70:73], v[18:33]
	v_exp_f32_e32 v106, v106
	v_exp_f32_e32 v107, v107
	v_exp_f32_e32 v108, v108
	v_exp_f32_e32 v109, v109
	s_waitcnt lgkmcnt(8)
	v_mfma_f32_32x32x16_bf16 v[34:49], v[2:5], v[74:77], v[34:49]
	v_exp_f32_e32 v110, v110
	v_exp_f32_e32 v111, v111
	v_exp_f32_e32 v112, v112
	v_exp_f32_e32 v113, v113
	s_waitcnt vmcnt(2) lgkmcnt(0)
	s_barrier
	s_add_i32 s30, s28, 0x2000
	s_cmpk_lg_i32 s28, 0x4000
	s_cselect_b32 s30, s30, 0
	v_add_u32_e32 v196, s29, v190
	ds_read_b64_tr_b16 v[178:179], v196 offset:24576
	ds_read_b64_tr_b16 v[180:181], v196 offset:25088
	s_waitcnt lgkmcnt(9)
	v_mfma_f32_32x32x16_bf16 v[82:97], v[78:81], v[162:165], v[50:65]
	v_add_f32_e32 v2, v114, v115
	v_add_f32_e32 v2, v116, v2
	v_add_f32_e32 v2, v117, v2
	v_add_f32_e32 v2, v118, v2
	v_add_f32_e32 v2, v119, v2
	v_cvt_pk_bf16_f32 v146, v114, v115
	v_cvt_pk_bf16_f32 v147, v116, v117
	ds_read_b64_tr_b16 v[182:183], v196 offset:28672
	ds_read_b64_tr_b16 v[184:185], v196 offset:29184
	s_waitcnt lgkmcnt(10)
	v_mfma_f32_32x32x16_bf16 v[66:81], v[134:137], v[162:165], v[50:65]
	v_add_f32_e32 v2, v120, v2
	v_add_f32_e32 v2, v121, v2
	v_add_f32_e32 v2, v122, v2
	v_add_f32_e32 v2, v123, v2
	v_cvt_pk_bf16_f32 v148, v118, v119
	v_cvt_pk_bf16_f32 v149, v120, v121
	ds_read_b64_tr_b16 v[114:115], v196 offset:25600
	ds_read_b64_tr_b16 v[116:117], v196 offset:26112
	s_waitcnt lgkmcnt(11)
	v_mfma_f32_32x32x16_bf16 v[82:97], v[138:141], v[158:161], v[82:97]
	v_add_f32_e32 v2, v124, v2
	v_add_f32_e32 v2, v125, v2
	v_add_f32_e32 v2, v126, v2
	v_add_f32_e32 v2, v127, v2
	v_cvt_pk_bf16_f32 v10, v122, v123
	v_cvt_pk_bf16_f32 v11, v124, v125
	ds_read_b64_tr_b16 v[118:119], v196 offset:29696
	ds_read_b64_tr_b16 v[120:121], v196 offset:30208
	s_waitcnt lgkmcnt(12)
	v_mfma_f32_32x32x16_bf16 v[66:81], v[142:145], v[158:161], v[66:81]
	v_add_f32_e32 v2, v128, v2
	v_add_f32_e32 v2, v129, v2
	v_add_f32_e32 v2, v98, v2
	v_add_f32_e32 v2, v99, v2
	v_cvt_pk_bf16_f32 v12, v126, v127
	v_cvt_pk_bf16_f32 v13, v128, v129
	ds_read_b64_tr_b16 v[122:123], v196 offset:26624
	ds_read_b64_tr_b16 v[124:125], v196 offset:27136
	s_waitcnt lgkmcnt(13)
	v_mfma_f32_32x32x16_bf16 v[82:97], v[166:169], v[154:157], v[82:97]
	v_add_f32_e32 v2, v100, v2
	v_add_f32_e32 v2, v101, v2
	v_add_f32_e32 v2, v102, v2
	v_add_f32_e32 v2, v103, v2
	v_cvt_pk_bf16_f32 v6, v98, v99
	v_cvt_pk_bf16_f32 v7, v100, v101
	ds_read_b64_tr_b16 v[126:127], v196 offset:30720
	ds_read_b64_tr_b16 v[128:129], v196 offset:31232
	s_waitcnt lgkmcnt(14)
	v_mfma_f32_32x32x16_bf16 v[66:81], v[170:173], v[154:157], v[66:81]
	v_add_f32_e32 v2, v104, v2
	v_add_f32_e32 v2, v105, v2
	v_add_f32_e32 v2, v106, v2
	v_add_f32_e32 v2, v107, v2
	v_cvt_pk_bf16_f32 v8, v102, v103
	v_cvt_pk_bf16_f32 v9, v104, v105
	ds_read_b64_tr_b16 v[102:103], v196 offset:27648
	ds_read_b64_tr_b16 v[104:105], v196 offset:28160
	s_waitcnt lgkmcnt(14)
	v_mfma_f32_32x32x16_bf16 v[82:97], v[174:177], v[150:153], v[82:97]
	v_add_f32_e32 v2, v108, v2
	v_add_f32_e32 v2, v109, v2
	v_add_f32_e32 v2, v110, v2
	v_add_f32_e32 v98, v111, v2
	v_cvt_pk_bf16_f32 v2, v106, v107
	v_cvt_pk_bf16_f32 v3, v108, v109
	ds_read_b64_tr_b16 v[106:107], v196 offset:31744
	ds_read_b64_tr_b16 v[108:109], v196 offset:32256
	v_mfma_f32_32x32x16_bf16 v[66:81], v[130:133], v[150:153], v[66:81]
	v_add_f32_e32 v4, v112, v98
	v_add_f32_e32 v4, v113, v4
	v_add_f32_e32 v196, 0, v4
	v_cvt_pk_bf16_f32 v4, v110, v111
	v_cvt_pk_bf16_f32 v5, v112, v113
	s_add_u32 s38, s31, 0xe568300
	s_addc_u32 s39, s34, 0
	s_add_i32 s29, s28, s26
	s_mov_b32 s31, m0
	s_mov_b32 m0, s29
	s_nop 0
	global_load_lds_dwordx4 v193, s[38:39]
	s_mov_b32 m0, s31
	s_add_u32 s34, s35, 0xe4d9100
	s_addc_u32 s35, s36, 0
	s_add_i32 s29, s30, s20
	s_mov_b32 s31, m0
	s_mov_b32 m0, s29
	s_nop 0
	global_load_lds_dwordx4 v192, s[34:35]
	s_mov_b32 m0, s31
	s_waitcnt lgkmcnt(14)
	v_mfma_f32_32x32x16_bf16 v[18:33], v[146:149], v[178:181], v[18:33]
	v_exp_f32_e32 v82, v82
	v_exp_f32_e32 v83, v83
	v_exp_f32_e32 v84, v84
	v_exp_f32_e32 v85, v85
	s_waitcnt lgkmcnt(12)
; #define WAIT_BAR(N) asm volatile("s_waitcnt vmcnt(" #N ") lgkmcnt(0)\n\ts_barrier" ::: "memory")
; #define RESC() do { if (resc) { asm volatile("s_waitcnt lgkmcnt(0)" ::: "memory"); \
;       _Pragma("unroll") for (int d_ = 0; d_ < 2; ++d_) _Pragma("unroll") for (int r = 0; r < 16; ++r) o[d_][r] *= wsf[crow(r, hi)]; } } while (0)
; #define ROT() do { sl_prev = sl_cur; sl_cur = sl_next; sl_next = (sl_next == (NSLOT - 1) * SLOTB) ? 0 : sl_next + SLOTB; } while (0)
; #define ENDW(tt) do { if ((tt) + 3 < NT) { WAIT_BAR(2); } else if ((tt) + 2 < NT) { WAIT_BAR(1); } else { WAIT_BAR(0); } } while (0)
;     ...
;     for (; t + 5 < NT; t += 2) {
;         STEP(pB0, pB1, pA0, pA1, t, true, true, true);     WAIT_BAR(2); RESC(); ROT();
;         STEP(pA0, pA1, pB0, pB1, t + 1, true, true, true); WAIT_BAR(2); RESC(); ROT();
;     }
;     ...
;     for (; t + 1 < NT; t += 2) {
;         STEP(pB0, pB1, pA0, pA1, t, (t + 3 < NT), (t + 1 < NT), (t + 1 < NT));         ENDW(t);     RESC(); ROT();
;         STEP(pA0, pA1, pB0, pB1, t + 1, (t + 4 < NT), (t + 2 < NT), (t + 2 < NT));     ENDW(t + 1); RESC(); ROT();
;     }
;     STEP(pB0, pB1, pA0, pA1, NT - 1, false, false, false); RESC();
	v_mfma_f32_32x32x16_bf16 v[34:49], v[146:149], v[182:185], v[34:49]
	v_exp_f32_e32 v86, v86
	v_exp_f32_e32 v87, v87
	v_exp_f32_e32 v88, v88
	v_exp_f32_e32 v89, v89
	v_add_u32_e32 v110, s30, v191
	ds_read_b128 v[98:101], v110
	ds_read_b128 v[170:173], v110 offset:512
	s_waitcnt lgkmcnt(12)
	v_mfma_f32_32x32x16_bf16 v[18:33], v[10:13], v[114:117], v[18:33]
	v_exp_f32_e32 v90, v90
	v_exp_f32_e32 v91, v91
	v_exp_f32_e32 v92, v92
	v_exp_f32_e32 v93, v93
	ds_read_b128 v[174:177], v110 offset:2048
	ds_read_b128 v[166:169], v110 offset:2560
	s_waitcnt lgkmcnt(12)
	v_mfma_f32_32x32x16_bf16 v[34:49], v[10:13], v[118:121], v[34:49]
	v_exp_f32_e32 v94, v94
	v_exp_f32_e32 v95, v95
	v_exp_f32_e32 v96, v96
	v_exp_f32_e32 v97, v97
	ds_read_b128 v[142:145], v110 offset:4096
	ds_read_b128 v[138:141], v110 offset:4608
	s_waitcnt lgkmcnt(12)
	v_mfma_f32_32x32x16_bf16 v[18:33], v[6:9], v[122:125], v[18:33]
	v_exp_f32_e32 v66, v66
	v_exp_f32_e32 v67, v67
	v_exp_f32_e32 v68, v68
	v_exp_f32_e32 v69, v69
	ds_read_b128 v[134:137], v110 offset:6144
	ds_read_b128 v[130:133], v110 offset:6656
	s_waitcnt lgkmcnt(12)
	v_mfma_f32_32x32x16_bf16 v[34:49], v[6:9], v[126:129], v[34:49]
	v_exp_f32_e32 v70, v70
	v_exp_f32_e32 v71, v71
	v_exp_f32_e32 v72, v72
	v_exp_f32_e32 v73, v73
	s_waitcnt lgkmcnt(10)
	v_mfma_f32_32x32x16_bf16 v[18:33], v[2:5], v[102:105], v[18:33]
	v_exp_f32_e32 v74, v74
	v_exp_f32_e32 v75, v75
	v_exp_f32_e32 v76, v76
	v_exp_f32_e32 v77, v77
	s_waitcnt lgkmcnt(8)
	v_mfma_f32_32x32x16_bf16 v[34:49], v[2:5], v[106:109], v[34:49]
	v_exp_f32_e32 v78, v78
	v_exp_f32_e32 v79, v79
	v_exp_f32_e32 v80, v80
	v_exp_f32_e32 v81, v81
	s_add_i32 s34, s30, 0x2000
	s_cmpk_lg_i32 s30, 0x4000
	s_mov_b32 s31, s28
	s_cselect_b32 s28, s34, 0
	s_add_i32 s27, s27, 2
	s_add_u32 s23, s23, 0x90000
	s_addc_u32 s24, s24, 0
	s_waitcnt vmcnt(2) lgkmcnt(0)
	s_barrier
	s_add_u32 s2, s2, 0x90000
	v_add_f32_e32 v2, v194, v195
	s_addc_u32 s22, s22, 0
	s_mov_b32 s29, s30
	v_add_f32_e32 v194, v2, v196
	s_cmp_gt_u32 s27, s47
	s_cbranch_scc0 .LBB0_876
	s_and_b32 s2, s25, 0x3fffffc0
	s_lshl_b32 s2, s2, 2
	s_add_i32 s2, s2, 0
	ds_read_b64_tr_b16 v[182:183], v190 offset:24576
	ds_read_b64_tr_b16 v[184:185], v190 offset:25088
	v_add_f32_e32 v2, v82, v83
	v_add_f32_e32 v2, v84, v2
	v_add_f32_e32 v2, v85, v2
	v_add_f32_e32 v2, v86, v2
	v_add_f32_e32 v2, v87, v2
	v_cvt_pk_bf16_f32 v146, v82, v83
	v_cvt_pk_bf16_f32 v147, v84, v85
	s_waitcnt lgkmcnt(9)
	v_mfma_f32_32x32x16_bf16 v[114:129], v[98:101], v[162:165], v[50:65]
	ds_read_b64_tr_b16 v[178:179], v190 offset:28672
	ds_read_b64_tr_b16 v[180:181], v190 offset:29184
	v_add_f32_e32 v2, v88, v2
	v_add_f32_e32 v2, v89, v2
	v_add_f32_e32 v2, v90, v2
	v_add_f32_e32 v2, v91, v2
	v_cvt_pk_bf16_f32 v148, v86, v87
	v_cvt_pk_bf16_f32 v149, v88, v89
	s_waitcnt lgkmcnt(10)
	v_mfma_f32_32x32x16_bf16 v[98:113], v[170:173], v[162:165], v[50:65]
	ds_read_b64_tr_b16 v[82:83], v190 offset:25600
	ds_read_b64_tr_b16 v[84:85], v190 offset:26112
	v_add_f32_e32 v2, v92, v2
	v_add_f32_e32 v2, v93, v2
	v_add_f32_e32 v2, v94, v2
	v_add_f32_e32 v2, v95, v2
	v_cvt_pk_bf16_f32 v10, v90, v91
	v_cvt_pk_bf16_f32 v11, v92, v93
	s_waitcnt lgkmcnt(11)
	v_mfma_f32_32x32x16_bf16 v[114:129], v[174:177], v[158:161], v[114:129]
	ds_read_b64_tr_b16 v[86:87], v190 offset:29696
	ds_read_b64_tr_b16 v[88:89], v190 offset:30208
	v_add_f32_e32 v2, v96, v2
	v_add_f32_e32 v2, v97, v2
	v_add_f32_e32 v2, v66, v2
	v_add_f32_e32 v2, v67, v2
	v_cvt_pk_bf16_f32 v12, v94, v95
	v_cvt_pk_bf16_f32 v13, v96, v97
	s_waitcnt lgkmcnt(12)
	v_mfma_f32_32x32x16_bf16 v[98:113], v[166:169], v[158:161], v[98:113]
	ds_read_b64_tr_b16 v[90:91], v190 offset:26624
	ds_read_b64_tr_b16 v[92:93], v190 offset:27136
	v_add_f32_e32 v2, v68, v2
	v_add_f32_e32 v2, v69, v2
	v_add_f32_e32 v2, v70, v2
	v_add_f32_e32 v2, v71, v2
	v_cvt_pk_bf16_f32 v6, v66, v67
	v_cvt_pk_bf16_f32 v7, v68, v69
	s_waitcnt lgkmcnt(13)
	v_mfma_f32_32x32x16_bf16 v[114:129], v[142:145], v[154:157], v[114:129]
	ds_read_b64_tr_b16 v[66:67], v190 offset:30720
	ds_read_b64_tr_b16 v[68:69], v190 offset:31232
	v_add_f32_e32 v2, v72, v2
	v_add_f32_e32 v2, v73, v2
	v_add_f32_e32 v2, v74, v2
	v_add_f32_e32 v2, v75, v2
	v_cvt_pk_bf16_f32 v8, v70, v71
	v_cvt_pk_bf16_f32 v9, v72, v73
	s_waitcnt lgkmcnt(14)
	v_mfma_f32_32x32x16_bf16 v[98:113], v[138:141], v[154:157], v[98:113]
	ds_read_b64_tr_b16 v[70:71], v190 offset:27648
	ds_read_b64_tr_b16 v[72:73], v190 offset:28160
	v_add_f32_e32 v2, v76, v2
	v_add_f32_e32 v2, v77, v2
	v_add_f32_e32 v2, v78, v2
	v_add_f32_e32 v94, v79, v2
	v_cvt_pk_bf16_f32 v2, v74, v75
	v_cvt_pk_bf16_f32 v3, v76, v77
	s_waitcnt lgkmcnt(14)
	v_mfma_f32_32x32x16_bf16 v[114:129], v[134:137], v[150:153], v[114:129]
	ds_read_b64_tr_b16 v[74:75], v190 offset:31744
	ds_read_b64_tr_b16 v[76:77], v190 offset:32256
	v_add_f32_e32 v4, v80, v94
	v_add_f32_e32 v4, v81, v4
	v_add_f32_e32 v94, 0, v4
	v_cvt_pk_bf16_f32 v4, v78, v79
	v_cvt_pk_bf16_f32 v5, v80, v81
	v_mfma_f32_32x32x16_bf16 v[98:113], v[130:133], v[150:153], v[98:113]
	s_add_u32 s16, s14, 0x2490000
	s_addc_u32 s17, s15, 0
	s_cmp_lg_u32 0, -1
	s_cselect_b32 s23, 0, 0
	s_add_i32 s22, s23, s21
	s_add_i32 s24, s22, 0x2000
	s_mov_b32 s25, m0
	s_mov_b32 m0, s24
	s_nop 0
	global_load_lds_dwordx4 v193, s[16:17]
	s_mov_b32 m0, s25
	s_add_u32 s24, s12, 0x2400000
	s_addc_u32 s25, s13, 0
	s_add_i32 s16, s23, 0xa000
	s_add_i32 s17, s21, s16
	s_mov_b32 s21, m0
	s_mov_b32 m0, s17
	s_nop 0
	global_load_lds_dwordx4 v192, s[24:25]
	s_mov_b32 m0, s21
	v_add_f32_e32 v194, v194, v94
	s_waitcnt lgkmcnt(14)
	v_mfma_f32_32x32x16_bf16 v[18:33], v[146:149], v[182:185], v[18:33]
	v_exp_f32_e32 v114, v114
	v_exp_f32_e32 v115, v115
	v_exp_f32_e32 v116, v116
	v_exp_f32_e32 v117, v117
	s_waitcnt lgkmcnt(12)
; #define RESC() do { if (resc) { asm volatile("s_waitcnt lgkmcnt(0)" ::: "memory"); \
;       _Pragma("unroll") for (int d_ = 0; d_ < 2; ++d_) _Pragma("unroll") for (int r = 0; r < 16; ++r) o[d_][r] *= wsf[crow(r, hi)]; } } while (0)
; #define ROT() do { sl_prev = sl_cur; sl_cur = sl_next; sl_next = (sl_next == (NSLOT - 1) * SLOTB) ? 0 : sl_next + SLOTB; } while (0)
; #define ENDW(tt) do { if ((tt) + 3 < NT) { WAIT_BAR(2); } else if ((tt) + 2 < NT) { WAIT_BAR(1); } else { WAIT_BAR(0); } } while (0)
;     ...
;     for (; t + 1 < NT; t += 2) {
;         STEP(pB0, pB1, pA0, pA1, t, (t + 3 < NT), (t + 1 < NT), (t + 1 < NT));         ENDW(t);     RESC(); ROT();
;         STEP(pA0, pA1, pB0, pB1, t + 1, (t + 4 < NT), (t + 2 < NT), (t + 2 < NT));     ENDW(t + 1); RESC(); ROT();
;     }
;     STEP(pB0, pB1, pA0, pA1, NT - 1, false, false, false); RESC();
	v_mfma_f32_32x32x16_bf16 v[34:49], v[146:149], v[178:181], v[34:49]
	v_exp_f32_e32 v118, v118
	v_exp_f32_e32 v119, v119
	v_exp_f32_e32 v120, v120
	v_exp_f32_e32 v121, v121
	ds_read_b128 v[78:81], v191 offset:16384
	ds_read_b128 v[94:97], v191 offset:16896
	s_waitcnt lgkmcnt(12)
	v_mfma_f32_32x32x16_bf16 v[18:33], v[10:13], v[82:85], v[18:33]
	v_exp_f32_e32 v122, v122
	v_exp_f32_e32 v123, v123
	v_exp_f32_e32 v124, v124
	v_exp_f32_e32 v125, v125
	ds_read_b128 v[166:169], v191 offset:18432
	ds_read_b128 v[170:173], v191 offset:18944
	s_waitcnt lgkmcnt(12)
	v_mfma_f32_32x32x16_bf16 v[34:49], v[10:13], v[86:89], v[34:49]
	v_exp_f32_e32 v126, v126
	v_exp_f32_e32 v127, v127
	v_exp_f32_e32 v128, v128
	v_exp_f32_e32 v129, v129
	ds_read_b128 v[174:177], v191 offset:20480
	ds_read_b128 v[178:181], v191 offset:20992
	s_waitcnt lgkmcnt(12)
	v_mfma_f32_32x32x16_bf16 v[18:33], v[6:9], v[90:93], v[18:33]
	v_exp_f32_e32 v98, v98
	v_exp_f32_e32 v99, v99
	v_exp_f32_e32 v100, v100
	v_exp_f32_e32 v101, v101
	ds_read_b128 v[90:93], v191 offset:22528
	ds_read_b128 v[82:85], v191 offset:23040
	s_waitcnt lgkmcnt(12)
	v_mfma_f32_32x32x16_bf16 v[34:49], v[6:9], v[66:69], v[34:49]
	v_exp_f32_e32 v102, v102
	v_exp_f32_e32 v103, v103
	v_exp_f32_e32 v104, v104
	v_exp_f32_e32 v105, v105
	s_waitcnt lgkmcnt(10)
	v_mfma_f32_32x32x16_bf16 v[18:33], v[2:5], v[70:73], v[18:33]
	v_exp_f32_e32 v106, v106
	v_exp_f32_e32 v107, v107
	v_exp_f32_e32 v108, v108
	v_exp_f32_e32 v109, v109
	s_waitcnt lgkmcnt(8)
	v_mfma_f32_32x32x16_bf16 v[34:49], v[2:5], v[74:77], v[34:49]
	v_exp_f32_e32 v110, v110
	v_exp_f32_e32 v111, v111
	v_exp_f32_e32 v112, v112
	v_exp_f32_e32 v113, v113
	s_waitcnt vmcnt(2) lgkmcnt(0)
	s_barrier
	ds_read_b64_tr_b16 v[182:183], v190 offset:32768
	ds_read_b64_tr_b16 v[184:185], v190 offset:33280
	v_add_f32_e32 v2, v114, v115
	v_add_f32_e32 v2, v116, v2
	v_add_f32_e32 v2, v117, v2
	v_add_f32_e32 v2, v118, v2
	v_add_f32_e32 v2, v119, v2
	v_cvt_pk_bf16_f32 v146, v114, v115
	v_cvt_pk_bf16_f32 v147, v116, v117
	s_waitcnt lgkmcnt(9)
	v_mfma_f32_32x32x16_bf16 v[130:145], v[78:81], v[162:165], v[50:65]
	ds_read_b64_tr_b16 v[114:115], v190 offset:36864
	ds_read_b64_tr_b16 v[116:117], v190 offset:37376
	s_waitcnt lgkmcnt(10)
	v_mfma_f32_32x32x16_bf16 v[66:81], v[94:97], v[162:165], v[50:65]
	v_add_f32_e32 v2, v120, v2
	v_add_f32_e32 v2, v121, v2
	v_add_f32_e32 v2, v122, v2
	v_add_f32_e32 v2, v123, v2
	v_cvt_pk_bf16_f32 v148, v118, v119
	v_cvt_pk_bf16_f32 v149, v120, v121
	ds_read_b64_tr_b16 v[86:87], v190 offset:33792
	ds_read_b64_tr_b16 v[88:89], v190 offset:34304
	v_add_f32_e32 v2, v124, v2
	v_add_f32_e32 v2, v125, v2
	v_add_f32_e32 v2, v126, v2
	v_add_f32_e32 v2, v127, v2
	v_cvt_pk_bf16_f32 v10, v122, v123
	v_cvt_pk_bf16_f32 v11, v124, v125
	s_waitcnt lgkmcnt(11)
	v_mfma_f32_32x32x16_bf16 v[130:145], v[166:169], v[158:161], v[130:145]
	ds_read_b64_tr_b16 v[94:95], v190 offset:37888
	ds_read_b64_tr_b16 v[96:97], v190 offset:38400
	s_waitcnt lgkmcnt(12)
	v_mfma_f32_32x32x16_bf16 v[66:81], v[170:173], v[158:161], v[66:81]
	v_add_f32_e32 v2, v128, v2
	v_add_f32_e32 v2, v129, v2
	v_add_f32_e32 v2, v98, v2
	v_add_f32_e32 v2, v99, v2
	v_cvt_pk_bf16_f32 v12, v126, v127
	v_cvt_pk_bf16_f32 v13, v128, v129
	ds_read_b64_tr_b16 v[118:119], v190 offset:34816
	ds_read_b64_tr_b16 v[120:121], v190 offset:35328
	v_add_f32_e32 v2, v100, v2
	v_add_f32_e32 v2, v101, v2
	v_add_f32_e32 v2, v102, v2
	v_add_f32_e32 v2, v103, v2
	v_cvt_pk_bf16_f32 v6, v98, v99
	v_cvt_pk_bf16_f32 v7, v100, v101
	s_waitcnt lgkmcnt(13)
	v_mfma_f32_32x32x16_bf16 v[130:145], v[174:177], v[154:157], v[130:145]
	ds_read_b64_tr_b16 v[122:123], v190 offset:38912
	ds_read_b64_tr_b16 v[124:125], v190 offset:39424
	s_waitcnt lgkmcnt(14)
	v_mfma_f32_32x32x16_bf16 v[66:81], v[178:181], v[154:157], v[66:81]
	v_add_f32_e32 v2, v104, v2
	v_add_f32_e32 v2, v105, v2
	v_add_f32_e32 v2, v106, v2
	v_add_f32_e32 v2, v107, v2
	v_cvt_pk_bf16_f32 v8, v102, v103
	v_cvt_pk_bf16_f32 v9, v104, v105
	ds_read_b64_tr_b16 v[102:103], v190 offset:35840
	ds_read_b64_tr_b16 v[104:105], v190 offset:36352
	v_add_f32_e32 v2, v108, v2
	v_add_f32_e32 v2, v109, v2
	v_add_f32_e32 v2, v110, v2
	v_add_f32_e32 v98, v111, v2
	v_cvt_pk_bf16_f32 v2, v106, v107
	v_cvt_pk_bf16_f32 v3, v108, v109
	s_waitcnt lgkmcnt(14)
	v_mfma_f32_32x32x16_bf16 v[130:145], v[90:93], v[150:153], v[130:145]
	ds_read_b64_tr_b16 v[90:91], v190 offset:39936
	ds_read_b64_tr_b16 v[92:93], v190 offset:40448
	v_mfma_f32_32x32x16_bf16 v[66:81], v[82:85], v[150:153], v[66:81]
	v_add_f32_e32 v4, v112, v98
	v_add_f32_e32 v4, v113, v4
	v_add_f32_e32 v82, 0, v4
	v_cvt_pk_bf16_f32 v4, v110, v111
	v_cvt_pk_bf16_f32 v5, v112, v113
	s_add_u32 s14, s14, 0x24d8000
	s_addc_u32 s15, s15, 0
	s_add_i32 s21, s22, 0x4000
	s_mov_b32 s23, m0
	s_mov_b32 m0, s21
	s_nop 0
	global_load_lds_dwordx4 v193, s[14:15]
	s_mov_b32 m0, s23
	s_add_u32 s14, s12, 0x2448000
	s_addc_u32 s15, s13, 0
	s_mov_b32 s21, m0
	s_mov_b32 m0, s20
	s_nop 0
	global_load_lds_dwordx4 v192, s[14:15]
	s_mov_b32 m0, s21
	v_add_f32_e32 v194, v194, v82
	s_waitcnt lgkmcnt(14)
	v_mfma_f32_32x32x16_bf16 v[18:33], v[146:149], v[182:185], v[18:33]
	v_exp_f32_e32 v130, v130
	v_exp_f32_e32 v131, v131
	v_exp_f32_e32 v132, v132
	v_exp_f32_e32 v133, v133
	s_waitcnt lgkmcnt(12)
	v_mfma_f32_32x32x16_bf16 v[34:49], v[146:149], v[114:117], v[34:49]
	v_exp_f32_e32 v134, v134
	v_exp_f32_e32 v135, v135
	v_exp_f32_e32 v136, v136
	v_exp_f32_e32 v137, v137
	ds_read_b128 v[82:85], v191
	ds_read_b128 v[106:109], v191 offset:512
	s_waitcnt lgkmcnt(12)
	v_mfma_f32_32x32x16_bf16 v[18:33], v[10:13], v[86:89], v[18:33]
	v_exp_f32_e32 v138, v138
	v_exp_f32_e32 v139, v139
	v_exp_f32_e32 v140, v140
	v_exp_f32_e32 v141, v141
	ds_read_b128 v[110:113], v191 offset:2048
	ds_read_b128 v[166:169], v191 offset:2560
	s_waitcnt lgkmcnt(12)
	v_mfma_f32_32x32x16_bf16 v[34:49], v[10:13], v[94:97], v[34:49]
	v_exp_f32_e32 v142, v142
	v_exp_f32_e32 v143, v143
	v_exp_f32_e32 v144, v144
	v_exp_f32_e32 v145, v145
	ds_read_b128 v[170:173], v191 offset:4096
	ds_read_b128 v[174:177], v191 offset:4608
	s_waitcnt lgkmcnt(12)
	v_mfma_f32_32x32x16_bf16 v[18:33], v[6:9], v[118:121], v[18:33]
	v_exp_f32_e32 v66, v66
	v_exp_f32_e32 v67, v67
	v_exp_f32_e32 v68, v68
	v_exp_f32_e32 v69, v69
	ds_read_b128 v[178:181], v191 offset:6144
	ds_read_b128 v[98:101], v191 offset:6656
	s_waitcnt lgkmcnt(12)
	v_mfma_f32_32x32x16_bf16 v[34:49], v[6:9], v[122:125], v[34:49]
	v_exp_f32_e32 v70, v70
	v_exp_f32_e32 v71, v71
	v_exp_f32_e32 v72, v72
	v_exp_f32_e32 v73, v73
	s_waitcnt lgkmcnt(10)
	v_mfma_f32_32x32x16_bf16 v[18:33], v[2:5], v[102:105], v[18:33]
	v_exp_f32_e32 v74, v74
	v_exp_f32_e32 v75, v75
	v_exp_f32_e32 v76, v76
	v_exp_f32_e32 v77, v77
	s_waitcnt lgkmcnt(8)
	v_mfma_f32_32x32x16_bf16 v[34:49], v[2:5], v[90:93], v[34:49]
	v_exp_f32_e32 v78, v78
	v_exp_f32_e32 v79, v79
	v_exp_f32_e32 v80, v80
	v_exp_f32_e32 v81, v81
	s_waitcnt vmcnt(2) lgkmcnt(0)
	s_barrier
; #define RESC() do { if (resc) { asm volatile("s_waitcnt lgkmcnt(0)" ::: "memory"); \
;       _Pragma("unroll") for (int d_ = 0; d_ < 2; ++d_) _Pragma("unroll") for (int r = 0; r < 16; ++r) o[d_][r] *= wsf[crow(r, hi)]; } } while (0)
; #define ROT() do { sl_prev = sl_cur; sl_cur = sl_next; sl_next = (sl_next == (NSLOT - 1) * SLOTB) ? 0 : sl_next + SLOTB; } while (0)
; #define ENDW(tt) do { if ((tt) + 3 < NT) { WAIT_BAR(2); } else if ((tt) + 2 < NT) { WAIT_BAR(1); } else { WAIT_BAR(0); } } while (0)
;     ...
;     for (; t + 1 < NT; t += 2) {
;         STEP(pB0, pB1, pA0, pA1, t, (t + 3 < NT), (t + 1 < NT), (t + 1 < NT));         ENDW(t);     RESC(); ROT();
;         STEP(pA0, pA1, pB0, pB1, t + 1, (t + 4 < NT), (t + 2 < NT), (t + 2 < NT));     ENDW(t + 1); RESC(); ROT();
;     }
;     STEP(pB0, pB1, pA0, pA1, NT - 1, false, false, false); RESC();
	ds_read_b64_tr_b16 v[102:103], v190 offset:40960
	ds_read_b64_tr_b16 v[104:105], v190 offset:41472
	v_add_f32_e32 v2, v130, v131
	v_add_f32_e32 v2, v132, v2
	v_add_f32_e32 v2, v133, v2
	v_add_f32_e32 v2, v134, v2
	v_add_f32_e32 v2, v135, v2
	v_cvt_pk_bf16_f32 v146, v130, v131
	v_cvt_pk_bf16_f32 v147, v132, v133
	s_waitcnt lgkmcnt(9)
	v_mfma_f32_32x32x16_bf16 v[114:129], v[82:85], v[162:165], v[50:65]
	ds_read_b64_tr_b16 v[130:131], v190 offset:45056
	ds_read_b64_tr_b16 v[132:133], v190 offset:45568
	v_add_f32_e32 v2, v136, v2
	v_add_f32_e32 v2, v137, v2
	v_add_f32_e32 v2, v138, v2
	v_add_f32_e32 v2, v139, v2
	v_cvt_pk_bf16_f32 v148, v134, v135
	v_cvt_pk_bf16_f32 v149, v136, v137
	s_waitcnt lgkmcnt(10)
	v_mfma_f32_32x32x16_bf16 v[82:97], v[106:109], v[162:165], v[50:65]
	ds_read_b64_tr_b16 v[106:107], v190 offset:41984
	ds_read_b64_tr_b16 v[108:109], v190 offset:42496
	v_add_f32_e32 v2, v140, v2
	v_add_f32_e32 v2, v141, v2
	v_add_f32_e32 v2, v142, v2
	v_add_f32_e32 v2, v143, v2
	v_cvt_pk_bf16_f32 v10, v138, v139
	v_cvt_pk_bf16_f32 v11, v140, v141
	s_waitcnt lgkmcnt(11)
	v_mfma_f32_32x32x16_bf16 v[114:129], v[110:113], v[158:161], v[114:129]
	ds_read_b64_tr_b16 v[110:111], v190 offset:46080
	ds_read_b64_tr_b16 v[112:113], v190 offset:46592
	v_add_f32_e32 v2, v144, v2
	v_add_f32_e32 v2, v145, v2
	v_add_f32_e32 v2, v66, v2
	v_add_f32_e32 v2, v67, v2
	v_cvt_pk_bf16_f32 v12, v142, v143
	v_cvt_pk_bf16_f32 v13, v144, v145
	s_waitcnt lgkmcnt(12)
	v_mfma_f32_32x32x16_bf16 v[82:97], v[166:169], v[158:161], v[82:97]
	ds_read_b64_tr_b16 v[134:135], v190 offset:43008
	ds_read_b64_tr_b16 v[136:137], v190 offset:43520
	v_add_f32_e32 v2, v68, v2
	v_add_f32_e32 v2, v69, v2
	v_add_f32_e32 v2, v70, v2
	v_add_f32_e32 v2, v71, v2
	v_cvt_pk_bf16_f32 v6, v66, v67
	v_cvt_pk_bf16_f32 v7, v68, v69
	s_waitcnt lgkmcnt(13)
	v_mfma_f32_32x32x16_bf16 v[114:129], v[170:173], v[154:157], v[114:129]
	ds_read_b64_tr_b16 v[66:67], v190 offset:47104
	ds_read_b64_tr_b16 v[68:69], v190 offset:47616
	v_add_f32_e32 v2, v72, v2
	v_add_f32_e32 v2, v73, v2
	v_add_f32_e32 v2, v74, v2
	v_add_f32_e32 v2, v75, v2
	v_cvt_pk_bf16_f32 v8, v70, v71
	v_cvt_pk_bf16_f32 v9, v72, v73
	s_waitcnt lgkmcnt(14)
	v_mfma_f32_32x32x16_bf16 v[82:97], v[174:177], v[154:157], v[82:97]
	ds_read_b64_tr_b16 v[70:71], v190 offset:44032
	ds_read_b64_tr_b16 v[72:73], v190 offset:44544
	v_add_f32_e32 v2, v76, v2
	v_add_f32_e32 v2, v77, v2
	v_add_f32_e32 v2, v78, v2
	v_add_f32_e32 v138, v79, v2
	v_cvt_pk_bf16_f32 v2, v74, v75
	v_cvt_pk_bf16_f32 v3, v76, v77
	s_waitcnt lgkmcnt(14)
	v_mfma_f32_32x32x16_bf16 v[114:129], v[178:181], v[150:153], v[114:129]
	ds_read_b64_tr_b16 v[74:75], v190 offset:48128
	ds_read_b64_tr_b16 v[76:77], v190 offset:48640
	v_add_f32_e32 v4, v80, v138
	v_add_f32_e32 v4, v81, v4
	v_mfma_f32_32x32x16_bf16 v[82:97], v[98:101], v[150:153], v[82:97]
	v_add_f32_e32 v98, 0, v4
	v_cvt_pk_bf16_f32 v4, v78, v79
	v_cvt_pk_bf16_f32 v5, v80, v81
	s_add_u32 s14, s12, 0x2490000
	s_addc_u32 s15, s13, 0
	s_add_i32 s22, s22, 0x8000
	s_mov_b32 s20, m0
	s_mov_b32 m0, s22
	s_nop 0
	global_load_lds_dwordx4 v192, s[14:15]
	s_mov_b32 m0, s20
	v_add_f32_e32 v182, v194, v98
	s_waitcnt lgkmcnt(14)
	v_mfma_f32_32x32x16_bf16 v[18:33], v[146:149], v[102:105], v[18:33]
	v_exp_f32_e32 v114, v114
	v_exp_f32_e32 v115, v115
	v_exp_f32_e32 v116, v116
	v_exp_f32_e32 v117, v117
	s_waitcnt lgkmcnt(12)
	v_mfma_f32_32x32x16_bf16 v[34:49], v[146:149], v[130:133], v[34:49]
	v_exp_f32_e32 v118, v118
	v_exp_f32_e32 v119, v119
	v_exp_f32_e32 v120, v120
	v_exp_f32_e32 v121, v121
	ds_read_b128 v[78:81], v191 offset:8192
	ds_read_b128 v[138:141], v191 offset:8704
	s_waitcnt lgkmcnt(12)
	v_mfma_f32_32x32x16_bf16 v[18:33], v[10:13], v[106:109], v[18:33]
	v_exp_f32_e32 v122, v122
	v_exp_f32_e32 v123, v123
	v_exp_f32_e32 v124, v124
	v_exp_f32_e32 v125, v125
	ds_read_b128 v[142:145], v191 offset:10240
	ds_read_b128 v[166:169], v191 offset:10752
	s_waitcnt lgkmcnt(12)
	v_mfma_f32_32x32x16_bf16 v[34:49], v[10:13], v[110:113], v[34:49]
	v_exp_f32_e32 v126, v126
	v_exp_f32_e32 v127, v127
	v_exp_f32_e32 v128, v128
	v_exp_f32_e32 v129, v129
	ds_read_b128 v[170:173], v191 offset:12288
	ds_read_b128 v[174:177], v191 offset:12800
	s_waitcnt lgkmcnt(12)
	v_mfma_f32_32x32x16_bf16 v[18:33], v[6:9], v[134:137], v[18:33]
	v_exp_f32_e32 v82, v82
	v_exp_f32_e32 v83, v83
	v_exp_f32_e32 v84, v84
	v_exp_f32_e32 v85, v85
	ds_read_b128 v[134:137], v191 offset:14336
	ds_read_b128 v[130:133], v191 offset:14848
	s_waitcnt lgkmcnt(12)
	v_mfma_f32_32x32x16_bf16 v[34:49], v[6:9], v[66:69], v[34:49]
	v_exp_f32_e32 v86, v86
	v_exp_f32_e32 v87, v87
	v_exp_f32_e32 v88, v88
	v_exp_f32_e32 v89, v89
	s_waitcnt lgkmcnt(10)
	v_mfma_f32_32x32x16_bf16 v[18:33], v[2:5], v[70:73], v[18:33]
	v_exp_f32_e32 v90, v90
	v_exp_f32_e32 v91, v91
	v_exp_f32_e32 v92, v92
	v_exp_f32_e32 v93, v93
	s_waitcnt lgkmcnt(8)
	v_mfma_f32_32x32x16_bf16 v[34:49], v[2:5], v[74:77], v[34:49]
	v_exp_f32_e32 v94, v94
	v_exp_f32_e32 v95, v95
	v_exp_f32_e32 v96, v96
	v_exp_f32_e32 v97, v97
	s_waitcnt vmcnt(1) lgkmcnt(0)
	s_barrier
; #define RESC() do { if (resc) { asm volatile("s_waitcnt lgkmcnt(0)" ::: "memory"); \
;       _Pragma("unroll") for (int d_ = 0; d_ < 2; ++d_) _Pragma("unroll") for (int r = 0; r < 16; ++r) o[d_][r] *= wsf[crow(r, hi)]; } } while (0)
; #define ROT() do { sl_prev = sl_cur; sl_cur = sl_next; sl_next = (sl_next == (NSLOT - 1) * SLOTB) ? 0 : sl_next + SLOTB; } while (0)
; #define ENDW(tt) do { if ((tt) + 3 < NT) { WAIT_BAR(2); } else if ((tt) + 2 < NT) { WAIT_BAR(1); } else { WAIT_BAR(0); } } while (0)
;     ...
;     for (; t + 1 < NT; t += 2) {
;         STEP(pB0, pB1, pA0, pA1, t, (t + 3 < NT), (t + 1 < NT), (t + 1 < NT));         ENDW(t);     RESC(); ROT();
;         STEP(pA0, pA1, pB0, pB1, t + 1, (t + 4 < NT), (t + 2 < NT), (t + 2 < NT));     ENDW(t + 1); RESC(); ROT();
;     }
;     STEP(pB0, pB1, pA0, pA1, NT - 1, false, false, false); RESC();
	ds_read_b64_tr_b16 v[178:179], v190 offset:24576
	ds_read_b64_tr_b16 v[180:181], v190 offset:25088
	v_add_f32_e32 v2, v114, v115
	v_add_f32_e32 v2, v116, v2
	v_add_f32_e32 v2, v117, v2
	v_add_f32_e32 v2, v118, v2
	v_add_f32_e32 v2, v119, v2
	v_cvt_pk_bf16_f32 v146, v114, v115
	v_cvt_pk_bf16_f32 v147, v116, v117
	s_waitcnt lgkmcnt(9)
	v_mfma_f32_32x32x16_bf16 v[98:113], v[78:81], v[162:165], v[50:65]
	ds_read_b64_tr_b16 v[114:115], v190 offset:28672
	ds_read_b64_tr_b16 v[116:117], v190 offset:29184
	s_waitcnt lgkmcnt(10)
	v_mfma_f32_32x32x16_bf16 v[66:81], v[138:141], v[162:165], v[50:65]
	v_add_f32_e32 v2, v120, v2
	v_add_f32_e32 v2, v121, v2
	v_add_f32_e32 v2, v122, v2
	v_add_f32_e32 v2, v123, v2
	v_cvt_pk_bf16_f32 v148, v118, v119
	v_cvt_pk_bf16_f32 v149, v120, v121
	ds_read_b64_tr_b16 v[118:119], v190 offset:25600
	ds_read_b64_tr_b16 v[120:121], v190 offset:26112
	v_add_f32_e32 v2, v124, v2
	v_add_f32_e32 v2, v125, v2
	v_add_f32_e32 v2, v126, v2
	v_add_f32_e32 v2, v127, v2
	v_cvt_pk_bf16_f32 v10, v122, v123
	v_cvt_pk_bf16_f32 v11, v124, v125
	s_waitcnt lgkmcnt(11)
	v_mfma_f32_32x32x16_bf16 v[98:113], v[142:145], v[158:161], v[98:113]
	ds_read_b64_tr_b16 v[122:123], v190 offset:29696
	ds_read_b64_tr_b16 v[124:125], v190 offset:30208
	s_waitcnt lgkmcnt(12)
	v_mfma_f32_32x32x16_bf16 v[66:81], v[166:169], v[158:161], v[66:81]
	v_add_f32_e32 v2, v128, v2
	v_add_f32_e32 v2, v129, v2
	v_add_f32_e32 v2, v82, v2
	v_add_f32_e32 v2, v83, v2
	v_cvt_pk_bf16_f32 v12, v126, v127
	v_cvt_pk_bf16_f32 v13, v128, v129
	ds_read_b64_tr_b16 v[138:139], v190 offset:26624
	ds_read_b64_tr_b16 v[140:141], v190 offset:27136
	v_add_f32_e32 v2, v84, v2
	v_add_f32_e32 v2, v85, v2
	v_add_f32_e32 v2, v86, v2
	v_add_f32_e32 v2, v87, v2
	v_cvt_pk_bf16_f32 v6, v82, v83
	v_cvt_pk_bf16_f32 v7, v84, v85
	s_waitcnt lgkmcnt(13)
	v_mfma_f32_32x32x16_bf16 v[98:113], v[170:173], v[154:157], v[98:113]
	ds_read_b64_tr_b16 v[82:83], v190 offset:30720
	ds_read_b64_tr_b16 v[84:85], v190 offset:31232
	s_waitcnt lgkmcnt(14)
	v_mfma_f32_32x32x16_bf16 v[66:81], v[174:177], v[154:157], v[66:81]
	v_add_f32_e32 v2, v88, v2
	v_add_f32_e32 v2, v89, v2
	v_add_f32_e32 v2, v90, v2
	v_add_f32_e32 v2, v91, v2
	v_cvt_pk_bf16_f32 v8, v86, v87
	v_cvt_pk_bf16_f32 v9, v88, v89
	ds_read_b64_tr_b16 v[86:87], v190 offset:27648
	ds_read_b64_tr_b16 v[88:89], v190 offset:28160
	v_add_f32_e32 v2, v92, v2
	v_add_f32_e32 v2, v93, v2
	v_add_f32_e32 v2, v94, v2
	v_add_f32_e32 v126, v95, v2
	v_cvt_pk_bf16_f32 v2, v90, v91
	v_cvt_pk_bf16_f32 v3, v92, v93
	s_waitcnt lgkmcnt(14)
	v_mfma_f32_32x32x16_bf16 v[98:113], v[134:137], v[150:153], v[98:113]
	ds_read_b64_tr_b16 v[90:91], v190 offset:31744
	ds_read_b64_tr_b16 v[92:93], v190 offset:32256
	v_mfma_f32_32x32x16_bf16 v[66:81], v[130:133], v[150:153], v[66:81]
	v_add_f32_e32 v4, v96, v126
	v_add_f32_e32 v4, v97, v4
	v_add_f32_e32 v126, 0, v4
	v_cvt_pk_bf16_f32 v4, v94, v95
	v_cvt_pk_bf16_f32 v5, v96, v97
	s_add_u32 s12, s12, 0x24d8000
	s_addc_u32 s13, s13, 0
	s_mov_b32 s14, m0
	s_mov_b32 m0, s17
	s_nop 0
	global_load_lds_dwordx4 v192, s[12:13]
	s_mov_b32 m0, s14
	v_add_f32_e32 v126, v182, v126
	s_waitcnt lgkmcnt(14)
	v_mfma_f32_32x32x16_bf16 v[18:33], v[146:149], v[178:181], v[18:33]
	v_exp_f32_e32 v98, v98
	v_exp_f32_e32 v99, v99
	v_exp_f32_e32 v100, v100
	v_exp_f32_e32 v101, v101
	s_waitcnt lgkmcnt(12)
	v_mfma_f32_32x32x16_bf16 v[34:49], v[146:149], v[114:117], v[34:49]
	v_exp_f32_e32 v102, v102
	v_exp_f32_e32 v103, v103
	v_exp_f32_e32 v104, v104
	v_exp_f32_e32 v105, v105
	ds_read_b128 v[128:131], v191 offset:16384
	ds_read_b128 v[132:135], v191 offset:16896
	s_waitcnt lgkmcnt(12)
	v_mfma_f32_32x32x16_bf16 v[18:33], v[10:13], v[118:121], v[18:33]
	v_exp_f32_e32 v106, v106
	v_exp_f32_e32 v107, v107
	v_exp_f32_e32 v108, v108
	v_exp_f32_e32 v109, v109
	ds_read_b128 v[142:145], v191 offset:18432
	ds_read_b128 v[166:169], v191 offset:18944
	s_waitcnt lgkmcnt(12)
	v_mfma_f32_32x32x16_bf16 v[34:49], v[10:13], v[122:125], v[34:49]
	v_exp_f32_e32 v110, v110
	v_exp_f32_e32 v111, v111
	v_exp_f32_e32 v112, v112
	v_exp_f32_e32 v113, v113
	ds_read_b128 v[170:173], v191 offset:20480
	ds_read_b128 v[174:177], v191 offset:20992
	s_waitcnt lgkmcnt(12)
	v_mfma_f32_32x32x16_bf16 v[18:33], v[6:9], v[138:141], v[18:33]
	v_exp_f32_e32 v66, v66
	v_exp_f32_e32 v67, v67
	v_exp_f32_e32 v68, v68
	v_exp_f32_e32 v69, v69
	ds_read_b128 v[136:139], v191 offset:22528
	ds_read_b128 v[122:125], v191 offset:23040
	s_waitcnt lgkmcnt(12)
	v_mfma_f32_32x32x16_bf16 v[34:49], v[6:9], v[82:85], v[34:49]
	v_exp_f32_e32 v70, v70
	v_exp_f32_e32 v71, v71
	v_exp_f32_e32 v72, v72
	v_exp_f32_e32 v73, v73
	s_waitcnt lgkmcnt(10)
	v_mfma_f32_32x32x16_bf16 v[18:33], v[2:5], v[86:89], v[18:33]
	v_exp_f32_e32 v74, v74
	v_exp_f32_e32 v75, v75
	v_exp_f32_e32 v76, v76
	v_exp_f32_e32 v77, v77
	s_waitcnt lgkmcnt(8)
	v_mfma_f32_32x32x16_bf16 v[34:49], v[2:5], v[90:93], v[34:49]
	v_exp_f32_e32 v78, v78
	v_exp_f32_e32 v79, v79
	v_exp_f32_e32 v80, v80
	v_exp_f32_e32 v81, v81
	s_waitcnt vmcnt(0) lgkmcnt(0)
	s_barrier
; #define RESC() do { if (resc) { asm volatile("s_waitcnt lgkmcnt(0)" ::: "memory"); \
;       _Pragma("unroll") for (int d_ = 0; d_ < 2; ++d_) _Pragma("unroll") for (int r = 0; r < 16; ++r) o[d_][r] *= wsf[crow(r, hi)]; } } while (0)
;     ...
;     STEP(pB0, pB1, pA0, pA1, NT - 1, false, false, false); RESC();
;     { float sacc = pB0[0] + pB0[1]; _Pragma("unroll") for (int r = 2; r < 16; ++r) sacc += pB0[r]; _Pragma("unroll") for (int r = 0; r < 16; ++r) sacc += pB1[r]; l_reg += sacc;
	ds_read_b64_tr_b16 v[114:115], v190 offset:32768
	ds_read_b64_tr_b16 v[116:117], v190 offset:33280
	v_add_f32_e32 v2, v98, v99
	v_add_f32_e32 v2, v100, v2
	v_add_f32_e32 v2, v101, v2
	v_add_f32_e32 v2, v102, v2
	v_add_f32_e32 v2, v103, v2
	v_cvt_pk_bf16_f32 v146, v98, v99
	v_cvt_pk_bf16_f32 v147, v100, v101
	s_waitcnt lgkmcnt(9)
	v_mfma_f32_32x32x16_bf16 v[82:97], v[128:131], v[162:165], v[50:65]
	ds_read_b64_tr_b16 v[98:99], v190 offset:36864
	ds_read_b64_tr_b16 v[100:101], v190 offset:37376
	v_add_f32_e32 v2, v104, v2
	v_add_f32_e32 v2, v105, v2
	v_add_f32_e32 v2, v106, v2
	v_add_f32_e32 v2, v107, v2
	v_cvt_pk_bf16_f32 v148, v102, v103
	v_cvt_pk_bf16_f32 v149, v104, v105
	s_waitcnt lgkmcnt(10)
	v_mfma_f32_32x32x16_bf16 v[50:65], v[132:135], v[162:165], v[50:65]
	ds_read_b64_tr_b16 v[118:119], v190 offset:33792
	ds_read_b64_tr_b16 v[120:121], v190 offset:34304
	v_add_f32_e32 v2, v108, v2
	v_add_f32_e32 v2, v109, v2
	v_add_f32_e32 v2, v110, v2
	v_add_f32_e32 v2, v111, v2
	v_cvt_pk_bf16_f32 v10, v106, v107
	v_cvt_pk_bf16_f32 v11, v108, v109
	s_waitcnt lgkmcnt(11)
	v_mfma_f32_32x32x16_bf16 v[82:97], v[142:145], v[158:161], v[82:97]
	ds_read_b64_tr_b16 v[102:103], v190 offset:37888
	ds_read_b64_tr_b16 v[104:105], v190 offset:38400
	v_add_f32_e32 v2, v112, v2
	v_add_f32_e32 v2, v113, v2
	v_add_f32_e32 v2, v66, v2
	v_add_f32_e32 v2, v67, v2
	v_cvt_pk_bf16_f32 v12, v110, v111
	v_cvt_pk_bf16_f32 v13, v112, v113
	s_waitcnt lgkmcnt(12)
	v_mfma_f32_32x32x16_bf16 v[50:65], v[166:169], v[158:161], v[50:65]
	ds_read_b64_tr_b16 v[106:107], v190 offset:34816
	ds_read_b64_tr_b16 v[108:109], v190 offset:35328
	v_add_f32_e32 v2, v68, v2
	v_add_f32_e32 v2, v69, v2
	v_add_f32_e32 v2, v70, v2
	v_add_f32_e32 v2, v71, v2
	v_cvt_pk_bf16_f32 v6, v66, v67
	v_cvt_pk_bf16_f32 v7, v68, v69
	s_waitcnt lgkmcnt(13)
	v_mfma_f32_32x32x16_bf16 v[82:97], v[170:173], v[154:157], v[82:97]
	ds_read_b64_tr_b16 v[66:67], v190 offset:38912
	ds_read_b64_tr_b16 v[68:69], v190 offset:39424
	v_add_f32_e32 v2, v72, v2
	v_add_f32_e32 v2, v73, v2
	v_add_f32_e32 v2, v74, v2
	v_add_f32_e32 v2, v75, v2
	v_cvt_pk_bf16_f32 v8, v70, v71
	v_cvt_pk_bf16_f32 v9, v72, v73
	s_waitcnt lgkmcnt(14)
	v_mfma_f32_32x32x16_bf16 v[50:65], v[174:177], v[154:157], v[50:65]
	ds_read_b64_tr_b16 v[110:111], v190 offset:35840
	ds_read_b64_tr_b16 v[112:113], v190 offset:36352
	v_add_f32_e32 v2, v76, v2
	v_add_f32_e32 v2, v77, v2
	v_add_f32_e32 v2, v78, v2
	v_add_f32_e32 v127, v79, v2
	v_cvt_pk_bf16_f32 v2, v74, v75
	v_cvt_pk_bf16_f32 v3, v76, v77
	s_waitcnt lgkmcnt(14)
	v_mfma_f32_32x32x16_bf16 v[82:97], v[136:139], v[150:153], v[82:97]
	ds_read_b64_tr_b16 v[70:71], v190 offset:39936
	ds_read_b64_tr_b16 v[72:73], v190 offset:40448
	v_add_f32_e32 v4, v80, v127
	v_add_f32_e32 v4, v81, v4
	v_add_f32_e32 v74, 0, v4
	v_cvt_pk_bf16_f32 v4, v78, v79
	v_cvt_pk_bf16_f32 v5, v80, v81
	v_mfma_f32_32x32x16_bf16 v[50:65], v[122:125], v[150:153], v[50:65]
	s_nop 3
	v_exp_f32_e32 v82, v82
	v_exp_f32_e32 v83, v83
	v_exp_f32_e32 v84, v84
	v_exp_f32_e32 v85, v85
	s_nop 0
	v_exp_f32_e32 v86, v86
	v_exp_f32_e32 v87, v87
	v_exp_f32_e32 v88, v88
	v_exp_f32_e32 v89, v89
	s_nop 0
	v_exp_f32_e32 v90, v90
	v_exp_f32_e32 v91, v91
	v_exp_f32_e32 v92, v92
	v_exp_f32_e32 v93, v93
	s_nop 0
	v_exp_f32_e32 v94, v94
	v_exp_f32_e32 v95, v95
	v_exp_f32_e32 v96, v96
	v_exp_f32_e32 v97, v97
	v_exp_f32_e32 v50, v50
	v_exp_f32_e32 v51, v51
	v_exp_f32_e32 v52, v52
	v_exp_f32_e32 v53, v53
	s_nop 0
	v_exp_f32_e32 v54, v54
	v_exp_f32_e32 v55, v55
	v_exp_f32_e32 v56, v56
	v_exp_f32_e32 v57, v57
	s_nop 0
	v_exp_f32_e32 v58, v58
	v_exp_f32_e32 v59, v59
	v_exp_f32_e32 v60, v60
	v_exp_f32_e32 v61, v61
	s_nop 0
	v_exp_f32_e32 v62, v62
	v_exp_f32_e32 v63, v63
	v_exp_f32_e32 v64, v64
	v_exp_f32_e32 v65, v65
	s_waitcnt lgkmcnt(14)
	v_mfma_f32_32x32x16_bf16 v[18:33], v[146:149], v[114:117], v[18:33]
	v_add_f32_e32 v75, v82, v83
	v_add_f32_e32 v75, v84, v75
	v_add_f32_e32 v75, v85, v75
	v_add_f32_e32 v75, v86, v75
	v_add_f32_e32 v75, v87, v75
	v_add_f32_e32 v75, v88, v75
	v_add_f32_e32 v75, v89, v75
	s_waitcnt lgkmcnt(12)
	v_mfma_f32_32x32x16_bf16 v[34:49], v[146:149], v[98:101], v[34:49]
	v_add_f32_e32 v75, v90, v75
	v_add_f32_e32 v75, v91, v75
	v_add_f32_e32 v75, v92, v75
	v_add_f32_e32 v75, v93, v75
	v_add_f32_e32 v75, v94, v75
	v_add_f32_e32 v75, v95, v75
	v_add_f32_e32 v75, v96, v75
	s_waitcnt lgkmcnt(10)
; #define AT_SBAR() __builtin_amdgcn_sched_barrier(0)
; #define SBAR() __builtin_amdgcn_sched_barrier(0)
; #define PKW(P, B) cvtpk_s(P[B], P[B + 1])
; __device__ __forceinline__ void pv(f32x16* o, int vb, bf16x8 pa0, bf16x8 pa1, bf16x8 pa2, bf16x8 pa3) {
; #pragma unroll
;     for (int d0 = 0; d0 < 2; ++d0) { s16x4 lo[4], hi[4];
; #pragma unroll
;         for (int ks = 0; ks < 4; ++ks) {
;             asm volatile("ds_read_b64_tr_b16 %0,%1 offset:%c2" : "=&v"(lo[ks]) : "v"(vb), "i"(d0 * 4096 + ks * 1024) : "memory");
;             asm volatile("ds_read_b64_tr_b16 %0,%1 offset:%c2" : "=&v"(hi[ks]) : "v"(vb), "i"(d0 * 4096 + ks * 1024 + 512) : "memory"); }
;         asm volatile("s_waitcnt lgkmcnt(0)" ::: "memory"); AT_SBAR();
;     ...
;         o[d0] = __builtin_amdgcn_mfma_f32_32x32x16_bf16(pa0, AT_PK(0), o[d0], 0, 0, 0);
;         o[d0] = __builtin_amdgcn_mfma_f32_32x32x16_bf16(pa1, AT_PK(1), o[d0], 0, 0, 0);
;         o[d0] = __builtin_amdgcn_mfma_f32_32x32x16_bf16(pa2, AT_PK(2), o[d0], 0, 0, 0);
;         o[d0] = __builtin_amdgcn_mfma_f32_32x32x16_bf16(pa3, AT_PK(3), o[d0], 0, 0, 0);
;     ...
;     }
;     ...
;     { float sacc = pB0[0] + pB0[1]; _Pragma("unroll") for (int r = 2; r < 16; ++r) sacc += pB0[r]; _Pragma("unroll") for (int r = 0; r < 16; ++r) sacc += pB1[r]; l_reg += sacc;
;       pw0 = (u32x4){PKW(pB0, 0), PKW(pB0, 2), PKW(pB0, 4), PKW(pB0, 6)}; pw1 = (u32x4){PKW(pB0, 8), PKW(pB0, 10), PKW(pB0, 12), PKW(pB0, 14)}; pw2 = (u32x4){PKW(pB1, 0), PKW(pB1, 2), PKW(pB1, 4), PKW(pB1, 6)}; pw3 = (u32x4){PKW(pB1, 8), PKW(pB1, 10), PKW(pB1, 12), PKW(pB1, 14)};
;       SBAR(); const int vb0 = (int)(lds0 + LDS_V) + ((lane >> 4) & 1) * 32 + (lane & 3) * 8 + (4 * hi + ((lane & 15) >> 2)) * 64;
;       at::pv(o, vb0 + sl_cur, PAF(0), PAF(1), PAF(2), PAF(3)); }
	v_mfma_f32_32x32x16_bf16 v[18:33], v[10:13], v[118:121], v[18:33]
	v_add_f32_e32 v75, v97, v75
	v_add_f32_e32 v75, v50, v75
	v_add_f32_e32 v75, v51, v75
	v_add_f32_e32 v75, v52, v75
	v_add_f32_e32 v75, v53, v75
	v_add_f32_e32 v75, v54, v75
	v_add_f32_e32 v75, v55, v75
	s_waitcnt lgkmcnt(8)
	v_mfma_f32_32x32x16_bf16 v[34:49], v[10:13], v[102:105], v[34:49]
	v_add_f32_e32 v75, v56, v75
	v_add_f32_e32 v75, v57, v75
	v_add_f32_e32 v75, v58, v75
	v_add_f32_e32 v75, v59, v75
	v_add_f32_e32 v75, v60, v75
	v_add_f32_e32 v75, v61, v75
	v_add_f32_e32 v75, v62, v75
	s_waitcnt lgkmcnt(6)
	v_mfma_f32_32x32x16_bf16 v[18:33], v[6:9], v[106:109], v[18:33]
	v_add_f32_e32 v75, v63, v75
	v_add_f32_e32 v75, v64, v75
	v_add_f32_e32 v75, v65, v75
	v_add_f32_e32 v74, v126, v74
	v_add_f32_e32 v74, v74, v75
	v_cvt_pk_bf16_f32 v76, v82, v83
	v_cvt_pk_bf16_f32 v77, v84, v85
	s_waitcnt lgkmcnt(4)
	v_mfma_f32_32x32x16_bf16 v[34:49], v[6:9], v[66:69], v[34:49]
	v_cvt_pk_bf16_f32 v78, v86, v87
	v_cvt_pk_bf16_f32 v79, v88, v89
	v_cvt_pk_bf16_f32 v10, v90, v91
	v_cvt_pk_bf16_f32 v11, v92, v93
	v_cvt_pk_bf16_f32 v12, v94, v95
	v_cvt_pk_bf16_f32 v13, v96, v97
	v_cvt_pk_bf16_f32 v6, v50, v51
	s_waitcnt lgkmcnt(2)
	v_mfma_f32_32x32x16_bf16 v[18:33], v[2:5], v[110:113], v[18:33]
	v_cvt_pk_bf16_f32 v7, v52, v53
	v_cvt_pk_bf16_f32 v8, v54, v55
	v_cvt_pk_bf16_f32 v9, v56, v57
	v_cvt_pk_bf16_f32 v50, v58, v59
	v_cvt_pk_bf16_f32 v51, v60, v61
	v_cvt_pk_bf16_f32 v52, v62, v63
	v_cvt_pk_bf16_f32 v53, v64, v65
	s_waitcnt lgkmcnt(0)
	v_mfma_f32_32x32x16_bf16 v[34:49], v[2:5], v[70:73], v[34:49]
	v_add_u32_e32 v2, s16, v188
	v_add3_u32 v66, v2, v187, v189
	ds_read_b64_tr_b16 v[2:3],v66 offset:0
	ds_read_b64_tr_b16 v[4:5],v66 offset:512
	ds_read_b64_tr_b16 v[54:55],v66 offset:1024
	ds_read_b64_tr_b16 v[56:57],v66 offset:1536
	ds_read_b64_tr_b16 v[58:59],v66 offset:2048
	ds_read_b64_tr_b16 v[60:61],v66 offset:2560
	ds_read_b64_tr_b16 v[62:63],v66 offset:3072
	ds_read_b64_tr_b16 v[64:65],v66 offset:3584
	s_waitcnt lgkmcnt(0)
	s_nop 0
	v_mfma_f32_32x32x16_bf16 v[18:33], v[76:79], v[2:5], v[18:33]
	ds_read_b64_tr_b16 v[2:3],v66 offset:4096
	ds_read_b64_tr_b16 v[4:5],v66 offset:4608
	v_mfma_f32_32x32x16_bf16 v[18:33], v[10:13], v[54:57], v[18:33]
	ds_read_b64_tr_b16 v[54:55],v66 offset:5120
	ds_read_b64_tr_b16 v[56:57],v66 offset:5632
	v_mfma_f32_32x32x16_bf16 v[18:33], v[6:9], v[58:61], v[18:33]
	ds_read_b64_tr_b16 v[58:59],v66 offset:6144
	ds_read_b64_tr_b16 v[60:61],v66 offset:6656
	v_mfma_f32_32x32x16_bf16 v[18:33], v[50:53], v[62:65], v[18:33]
	ds_read_b64_tr_b16 v[62:63],v66 offset:7168
	ds_read_b64_tr_b16 v[64:65],v66 offset:7680
	s_waitcnt lgkmcnt(0)
	v_mfma_f32_32x32x16_bf16 v[34:49], v[76:79], v[2:5], v[34:49]
	v_mfma_f32_32x32x16_bf16 v[34:49], v[10:13], v[54:57], v[34:49]
	v_mfma_f32_32x32x16_bf16 v[34:49], v[6:9], v[58:61], v[34:49]
	v_mfma_f32_32x32x16_bf16 v[34:49], v[50:53], v[62:65], v[34:49]
	s_setprio 0
	s_cmp_eq_u32 s100, 2
	s_cbranch_scc1 .Lgc_full
	s_nop 15
	s_sub_i32 s38, s48, 0x100
	s_lshl_b32 s40, s38, 6
	s_add_u32 s42, s76, 0x10000
	s_addc_u32 s43, s77, 0
	s_add_u32 s42, s42, s40
	s_addc_u32 s43, s43, 0
	s_mul_i32 s40, s38, 0x11000
	s_mul_i32 s39, s19, 0x2200
	s_add_u32 s40, s40, s39
	s_add_u32 s36, s76, 0xa200000
	s_addc_u32 s37, s77, 0
	s_add_u32 s36, s36, s40
	s_addc_u32 s37, s37, 0
	s_add_u32 s44, s36, 0x1000
	s_addc_u32 s45, s37, 0
	v_lshlrev_b32_e32 v116, 4, v15
	v_lshlrev_b32_e32 v115, 2, v15
	v_add_u32_e32 v115, 0x1000, v115
	v_mov_b32_e32 v120, 1
	s_cmp_eq_u32 s100, 1
	s_cbranch_scc1 .Lgc_second
	global_store_dwordx4 v116, v[18:21], s[36:37] sc0 sc1
	global_store_dwordx4 v116, v[22:25], s[36:37] offset:1024 sc0 sc1
	global_store_dwordx4 v116, v[26:29], s[36:37] offset:2048 sc0 sc1
	global_store_dwordx4 v116, v[30:33], s[36:37] offset:3072 sc0 sc1
	global_store_dwordx4 v116, v[34:37], s[44:45] sc0 sc1
	global_store_dwordx4 v116, v[38:41], s[44:45] offset:1024 sc0 sc1
	global_store_dwordx4 v116, v[42:45], s[44:45] offset:2048 sc0 sc1
	global_store_dwordx4 v116, v[46:49], s[44:45] offset:3072 sc0 sc1
	global_store_dword v115, v74, s[44:45] sc0 sc1
	s_waitcnt vmcnt(0)
	s_barrier
	s_and_saveexec_b64 s[44:45], s[62:63]
	s_cbranch_execz .Lgc_f1
	v_mov_b32_e32 v118, s42
	v_mov_b32_e32 v119, s43
	flat_atomic_add v[118:119], v120
